# LN+modulate loops: shift/scale loads issued at the top of the iteration with the row/gamma/beta loads instead of after the reductions
# baseline (speedup 1.0000x reference)
.LBB0_123:
	v_mov_b32_e32 v0, v139
	v_readlane_b32 s40, v247, 57
	v_ashrrev_i32_e32 v1, 5, v0
	v_and_b32_e32 v1, -2, v1
	v_add_u32_e32 v38, s12, v1
	v_lshlrev_b32_e32 v0, 2, v0
	v_ashrrev_i32_e32 v39, 31, v38
	v_and_b32_e32 v2, 0xfc, v0
	v_lshlrev_b64 v[0:1], 12, v[38:39]
	v_readlane_b32 s50, v246, 3
	v_readlane_b32 s51, v246, 4
	v_lshlrev_b32_e32 v136, 1, v2
	s_waitcnt vmcnt(8)
	v_add_u32_e32 v34, 1, v38
	v_lshl_add_u64 v[0:1], s[50:51], 0, v[0:1]
	v_lshl_add_u64 v[36:37], v[0:1], 0, v[136:137]
	global_load_dwordx2 v[42:43], v[36:37], off offset:2048
	global_load_dwordx2 v[44:45], v[36:37], off offset:2560
	global_load_dwordx2 v[46:47], v[36:37], off offset:3072
	global_load_dwordx2 v[48:49], v[36:37], off offset:3584
	v_ashrrev_i32_e32 v35, 31, v34
	v_lshlrev_b64 v[0:1], 12, v[34:35]
	v_lshl_add_u64 v[0:1], s[50:51], 0, v[0:1]
	v_lshl_add_u64 v[32:33], v[0:1], 0, v[136:137]
	global_load_dwordx2 v[50:51], v[32:33], off offset:2048
	global_load_dwordx2 v[52:53], v[32:33], off offset:2560
	global_load_dwordx2 v[54:55], v[32:33], off offset:3072
	global_load_dwordx2 v[56:57], v[32:33], off offset:3584
	v_cmp_lt_i32_e32 vcc, v179, v178
	v_lshlrev_b32_e32 v40, 2, v2
	global_load_dwordx4 v[24:27], v40, s[6:7]
	global_load_dwordx4 v[28:31], v40, s[8:9]
	global_load_dwordx4 v[16:19], v40, s[6:7] offset:1024
	global_load_dwordx4 v[20:23], v40, s[8:9] offset:1024
	global_load_dwordx4 v[8:11], v40, s[6:7] offset:2048
	global_load_dwordx4 v[12:15], v40, s[8:9] offset:2048
	global_load_dwordx4 v[0:3], v40, s[6:7] offset:3072
	global_load_dwordx4 v[4:7], v40, s[8:9] offset:3072
	v_mov_b32_e32 v252, v40
	v_mov_b32_e32 v253, v137
	v_cmp_lt_i32_e64 s[98:99], s16, v38
	v_add_u32_e32 v202, 0xfffff000, v38
	v_lshrrev_b32_e32 v202, 12, v202
	v_add_u32_e32 v202, 1, v202
	v_cndmask_b32_e64 v202, 0, v202, s[98:99]
	v_mov_b32_e32 v203, v137
	v_lshl_add_u64 v[202:203], v[202:203], 0, s[10:11]
	v_mov_b64_e32 v[204:205], s[56:57]
	v_mad_u64_u32 v[204:205], s[98:99], v202, s15, v[204:205]
	v_mad_i32_i24 v205, v203, s15, v205
	v_lshl_add_u64 v[202:203], v[204:205], 0, v[252:253]
	v_add_co_u32_e64 v206, s[98:99], s14, v202
	v_lshl_add_u64 v[208:209], v[202:203], 0, s[24:25]
	s_nop 1
	v_addc_co_u32_e64 v207, s[98:99], 0, v203, s[98:99]
	v_lshl_add_u64 v[252:253], v[202:203], 0, s[18:19]
	global_load_dwordx4 v[210:213], v[206:207], off offset:-4096
	global_load_dwordx4 v[214:217], v[206:207], off
	global_load_dwordx4 v[218:221], v[252:253], off offset:1024
	global_load_dwordx4 v[222:225], v[208:209], off offset:1024
	global_load_dwordx4 v[226:229], v[252:253], off offset:2048
	global_load_dwordx4 v[230:233], v[208:209], off offset:2048
	global_load_dwordx4 v[234:237], v[252:253], off offset:3072
	global_load_dwordx4 v[238:241], v[208:209], off offset:3072
	v_cndmask_b32_e32 v35, v176, v179, vcc
	v_cmp_lt_i32_e32 vcc, v180, v178
	v_lshlrev_b32_e32 v35, 2, v35
	v_mov_b32_e32 v41, v137
	v_cndmask_b32_e32 v39, v176, v180, vcc
	v_cmp_lt_i32_e32 vcc, v181, v178
	v_lshlrev_b32_e32 v39, 2, v39
	s_add_i32 s13, s13, s90
	v_cndmask_b32_e32 v58, v176, v181, vcc
	v_cmp_lt_i32_e32 vcc, v182, v178
	v_lshlrev_b32_e32 v86, 2, v58
	s_add_i32 s12, s12, s5
	v_cndmask_b32_e32 v58, v176, v182, vcc
	v_cmp_lt_i32_e32 vcc, v183, v178
	v_lshlrev_b32_e32 v87, 2, v58
	s_cmpk_gt_i32 s13, 0xbf
	v_cndmask_b32_e32 v58, v176, v183, vcc
	v_cmp_lt_i32_e32 vcc, v184, v178
	v_lshlrev_b32_e32 v88, 2, v58
	v_readlane_b32 s41, v247, 58
	v_cndmask_b32_e32 v58, v176, v184, vcc
	v_lshlrev_b32_e32 v89, 2, v58
	v_readlane_b32 s42, v247, 59
	v_readlane_b32 s43, v247, 60
	v_readlane_b32 s44, v247, 61
	v_readlane_b32 s45, v247, 62
	v_readlane_b32 s46, v247, 63
	v_readlane_b32 s47, v246, 0
	v_readlane_b32 s48, v246, 1
	v_readlane_b32 s49, v246, 2
	v_readlane_b32 s52, v246, 5
	v_readlane_b32 s53, v246, 6
	v_readlane_b32 s54, v246, 7
	v_readlane_b32 s55, v246, 8
	s_waitcnt vmcnt(23)
	v_lshlrev_b32_e32 v68, 16, v42
	s_waitcnt vmcnt(22)
	v_lshlrev_b32_e32 v66, 16, v44
	s_waitcnt vmcnt(21)
	v_lshlrev_b32_e32 v62, 16, v46
	s_waitcnt vmcnt(20)
	v_lshlrev_b32_e32 v60, 16, v48
	v_and_b32_e32 v61, 0xffff0000, v48
	v_and_b32_e32 v63, 0xffff0000, v46
	v_lshlrev_b32_e32 v58, 16, v49
	v_and_b32_e32 v59, 0xffff0000, v49
	v_lshlrev_b32_e32 v48, 16, v47
	v_and_b32_e32 v49, 0xffff0000, v47
	v_mov_b32_e32 v46, v62
	v_mov_b32_e32 v47, v60
	v_mov_b32_e32 v64, v63
	v_mov_b32_e32 v65, v61
	v_pk_add_f32 v[46:47], v[46:47], v[64:65]
	v_mov_b32_e32 v64, v48
	v_mov_b32_e32 v65, v58
	v_pk_add_f32 v[46:47], v[46:47], v[64:65]
	v_mov_b32_e32 v64, v49
	v_mov_b32_e32 v65, v59
	v_and_b32_e32 v67, 0xffff0000, v44
	v_and_b32_e32 v69, 0xffff0000, v42
	v_pk_add_f32 v[46:47], v[46:47], v[64:65]
	v_lshlrev_b32_e32 v64, 16, v45
	v_and_b32_e32 v65, 0xffff0000, v45
	v_lshlrev_b32_e32 v44, 16, v43
	v_and_b32_e32 v45, 0xffff0000, v43
	v_mov_b32_e32 v42, v68
	v_mov_b32_e32 v43, v66
	v_mov_b32_e32 v70, v69
	v_mov_b32_e32 v71, v67
	v_pk_add_f32 v[42:43], v[42:43], v[70:71]
	v_mov_b32_e32 v70, v44
	v_mov_b32_e32 v71, v64
	v_pk_add_f32 v[42:43], v[42:43], v[70:71]
	v_mov_b32_e32 v70, v45
	v_mov_b32_e32 v71, v65
	s_waitcnt vmcnt(16)
	v_lshlrev_b32_e32 v72, 16, v56
	v_and_b32_e32 v73, 0xffff0000, v56
	v_lshlrev_b32_e32 v74, 16, v54
	v_and_b32_e32 v75, 0xffff0000, v54
	v_pk_add_f32 v[42:43], v[42:43], v[70:71]
	v_lshlrev_b32_e32 v70, 16, v57
	v_and_b32_e32 v71, 0xffff0000, v57
	v_lshlrev_b32_e32 v56, 16, v55
	v_and_b32_e32 v57, 0xffff0000, v55
	v_mov_b32_e32 v54, v74
	v_mov_b32_e32 v55, v72
	v_mov_b32_e32 v76, v75
	v_mov_b32_e32 v77, v73
	v_pk_add_f32 v[54:55], v[54:55], v[76:77]
	v_mov_b32_e32 v76, v56
	v_mov_b32_e32 v77, v70
	v_pk_add_f32 v[54:55], v[54:55], v[76:77]
	v_mov_b32_e32 v76, v57
	v_mov_b32_e32 v77, v71
	v_lshlrev_b32_e32 v78, 16, v52
	v_and_b32_e32 v79, 0xffff0000, v52
	v_lshlrev_b32_e32 v80, 16, v50
	v_and_b32_e32 v81, 0xffff0000, v50
	v_pk_add_f32 v[54:55], v[54:55], v[76:77]
	v_lshlrev_b32_e32 v76, 16, v53
	v_and_b32_e32 v77, 0xffff0000, v53
	v_lshlrev_b32_e32 v52, 16, v51
	v_and_b32_e32 v53, 0xffff0000, v51
	v_mov_b32_e32 v50, v80
	v_mov_b32_e32 v51, v78
	v_mov_b32_e32 v82, v81
	v_mov_b32_e32 v83, v79
	v_pk_add_f32 v[50:51], v[50:51], v[82:83]
	v_mov_b32_e32 v82, v52
	v_mov_b32_e32 v83, v76
	v_pk_add_f32 v[50:51], v[50:51], v[82:83]
	v_mov_b32_e32 v82, v53
	v_mov_b32_e32 v83, v77
	v_pk_add_f32 v[50:51], v[50:51], v[82:83]
	v_add_f32_e32 v42, 0, v42
	v_add_f32_e32 v50, 0, v50
	v_add_f32_e32 v42, v42, v43
	v_add_f32_e32 v50, v50, v51
	v_add_f32_e32 v42, v42, v46
	v_add_f32_e32 v50, v50, v54
	v_add_f32_e32 v42, v42, v47
	v_add_f32_e32 v50, v50, v55
	ds_bpermute_b32 v43, v35, v42
	ds_bpermute_b32 v51, v35, v50
	s_waitcnt lgkmcnt(1)
	v_add_f32_e32 v42, v42, v43
	s_waitcnt lgkmcnt(0)
	v_add_f32_e32 v50, v50, v51
	ds_bpermute_b32 v43, v39, v42
	ds_bpermute_b32 v51, v39, v50
	s_waitcnt lgkmcnt(1)
	v_add_f32_e32 v42, v42, v43
	s_waitcnt lgkmcnt(0)
	v_add_f32_e32 v50, v50, v51
	ds_bpermute_b32 v43, v86, v42
	ds_bpermute_b32 v51, v86, v50
	s_waitcnt lgkmcnt(1)
	v_add_f32_e32 v42, v42, v43
	s_waitcnt lgkmcnt(0)
	v_add_f32_e32 v50, v50, v51
	ds_bpermute_b32 v43, v87, v42
	ds_bpermute_b32 v51, v87, v50
	s_waitcnt lgkmcnt(1)
	v_add_f32_e32 v42, v42, v43
	s_waitcnt lgkmcnt(0)
	v_add_f32_e32 v50, v50, v51
	ds_bpermute_b32 v43, v88, v42
	ds_bpermute_b32 v51, v88, v50
	s_waitcnt lgkmcnt(1)
	v_add_f32_e32 v42, v42, v43
	s_waitcnt lgkmcnt(0)
	v_add_f32_e32 v50, v50, v51
	ds_bpermute_b32 v43, v89, v42
	ds_bpermute_b32 v51, v89, v50
	s_waitcnt lgkmcnt(1)
	v_add_f32_e32 v42, v42, v43
	s_waitcnt lgkmcnt(0)
	v_add_f32_e32 v50, v50, v51
	v_mul_f32_e32 v42, 0x3a800000, v42
	v_mul_f32_e32 v50, 0x3a800000, v50
	v_pk_add_f32 v[46:47], v[68:69], v[42:43] op_sel_hi:[1,0] neg_lo:[0,1] neg_hi:[0,1]
	v_pk_add_f32 v[80:81], v[80:81], v[50:51] op_sel_hi:[1,0] neg_lo:[0,1] neg_hi:[0,1]
	v_mov_b32_e32 v83, v47
	v_mov_b32_e32 v82, v81
	v_mov_b32_e32 v54, v80
	v_mov_b32_e32 v55, v46
	v_pk_mul_f32 v[82:83], v[82:83], v[82:83]
	v_pk_add_f32 v[44:45], v[44:45], v[42:43] op_sel_hi:[1,0] neg_lo:[0,1] neg_hi:[0,1]
	v_pk_fma_f32 v[54:55], v[54:55], v[54:55], v[82:83]
	v_pk_add_f32 v[82:83], v[52:53], v[50:51] op_sel_hi:[1,0] neg_lo:[0,1] neg_hi:[0,1]
	v_mov_b32_e32 v53, v44
	v_mov_b32_e32 v52, v82
	v_pk_add_f32 v[66:67], v[66:67], v[42:43] op_sel_hi:[1,0] neg_lo:[0,1] neg_hi:[0,1]
	v_pk_add_f32 v[78:79], v[78:79], v[50:51] op_sel_hi:[1,0] neg_lo:[0,1] neg_hi:[0,1]
	v_pk_fma_f32 v[52:53], v[52:53], v[52:53], v[54:55]
	v_mov_b32_e32 v54, v83
	v_mov_b32_e32 v55, v45
	v_pk_fma_f32 v[52:53], v[54:55], v[54:55], v[52:53]
	v_mov_b32_e32 v54, v78
	v_mov_b32_e32 v55, v66
	v_pk_add_f32 v[64:65], v[64:65], v[42:43] op_sel_hi:[1,0] neg_lo:[0,1] neg_hi:[0,1]
	v_pk_add_f32 v[76:77], v[76:77], v[50:51] op_sel_hi:[1,0] neg_lo:[0,1] neg_hi:[0,1]
	v_pk_fma_f32 v[52:53], v[54:55], v[54:55], v[52:53]
	v_mov_b32_e32 v54, v79
	v_mov_b32_e32 v55, v67
	v_pk_fma_f32 v[52:53], v[54:55], v[54:55], v[52:53]
	v_mov_b32_e32 v54, v76
	v_mov_b32_e32 v55, v64
	v_pk_add_f32 v[62:63], v[62:63], v[42:43] op_sel_hi:[1,0] neg_lo:[0,1] neg_hi:[0,1]
	v_pk_add_f32 v[74:75], v[74:75], v[50:51] op_sel_hi:[1,0] neg_lo:[0,1] neg_hi:[0,1]
	v_pk_fma_f32 v[52:53], v[54:55], v[54:55], v[52:53]
	v_mov_b32_e32 v54, v77
	v_mov_b32_e32 v55, v65
	v_pk_fma_f32 v[52:53], v[54:55], v[54:55], v[52:53]
	v_mov_b32_e32 v54, v74
	v_mov_b32_e32 v55, v62
	v_pk_add_f32 v[68:69], v[48:49], v[42:43] op_sel_hi:[1,0] neg_lo:[0,1] neg_hi:[0,1]
	v_pk_add_f32 v[84:85], v[56:57], v[50:51] op_sel_hi:[1,0] neg_lo:[0,1] neg_hi:[0,1]
	v_pk_fma_f32 v[52:53], v[54:55], v[54:55], v[52:53]
	v_mov_b32_e32 v54, v75
	v_mov_b32_e32 v55, v63
	v_pk_add_f32 v[60:61], v[60:61], v[42:43] op_sel_hi:[1,0] neg_lo:[0,1] neg_hi:[0,1]
	v_pk_add_f32 v[72:73], v[72:73], v[50:51] op_sel_hi:[1,0] neg_lo:[0,1] neg_hi:[0,1]
	v_pk_fma_f32 v[52:53], v[54:55], v[54:55], v[52:53]
	v_mov_b32_e32 v54, v84
	v_mov_b32_e32 v55, v68
	v_pk_mul_f32 v[48:49], v[60:61], v[60:61]
	v_pk_mul_f32 v[56:57], v[72:73], v[72:73]
	v_pk_fma_f32 v[52:53], v[54:55], v[54:55], v[52:53]
	v_mov_b32_e32 v54, v85
	v_mov_b32_e32 v55, v69
	v_pk_add_f32 v[42:43], v[58:59], v[42:43] op_sel_hi:[1,0] neg_lo:[0,1] neg_hi:[0,1]
	v_pk_fma_f32 v[52:53], v[54:55], v[54:55], v[52:53]
	v_mov_b32_e32 v54, v56
	v_mov_b32_e32 v55, v48
	v_pk_add_f32 v[70:71], v[70:71], v[50:51] op_sel_hi:[1,0] neg_lo:[0,1] neg_hi:[0,1]
	v_pk_mul_f32 v[58:59], v[42:43], v[42:43]
	v_pk_add_f32 v[52:53], v[54:55], v[52:53]
	v_pk_mul_f32 v[50:51], v[70:71], v[70:71]
	v_mov_b32_e32 v48, v57
	v_pk_add_f32 v[48:49], v[48:49], v[52:53]
	v_mov_b32_e32 v52, v50
	v_mov_b32_e32 v53, v58
	v_pk_add_f32 v[48:49], v[52:53], v[48:49]
	v_mov_b32_e32 v58, v51
	v_pk_add_f32 v[48:49], v[58:59], v[48:49]
	v_mov_b32_e32 v50, v48
	v_mov_b32_e32 v51, v49
	s_nop 1
	v_permlane32_swap_b32_e32 v50, v48
	v_permlane32_swap_b32_e32 v51, v49
	v_pk_add_f32 v[48:49], v[48:49], v[50:51]
	v_mov_b32_e32 v50, v48
	v_mov_b32_e32 v51, v49
	s_nop 1
	v_permlane16_swap_b32_e32 v50, v48
	v_permlane16_swap_b32_e32 v51, v49
	v_pk_add_f32 v[48:49], v[48:49], v[50:51]
	s_nop 1
	v_add_f32_dpp v48, v48, v48 row_ror:8 row_mask:0xf bank_mask:0xf
	v_add_f32_dpp v49, v49, v49 row_ror:8 row_mask:0xf bank_mask:0xf
	s_nop 0
	v_add_f32_dpp v48, v48, v48 row_ror:4 row_mask:0xf bank_mask:0xf
	v_add_f32_dpp v49, v49, v49 row_ror:4 row_mask:0xf bank_mask:0xf
	s_nop 0
	v_add_f32_dpp v48, v48, v48 row_ror:2 row_mask:0xf bank_mask:0xf
	v_add_f32_dpp v49, v49, v49 row_ror:2 row_mask:0xf bank_mask:0xf
	s_nop 0
	v_add_f32_dpp v48, v48, v48 row_ror:1 row_mask:0xf bank_mask:0xf
	v_add_f32_dpp v49, v49, v49 row_ror:1 row_mask:0xf bank_mask:0xf
	s_nop 0
	v_pk_fma_f32 v[58:59], v[48:49], s[20:21], v[138:139] op_sel_hi:[1,0,0]
	s_nop 0
	v_mul_f32_e32 v35, 0x4b800000, v59
	v_cmp_gt_f32_e64 s[0:1], s33, v59
	v_cmp_gt_f32_e32 vcc, s33, v58
	s_nop 0
	v_cndmask_b32_e64 v35, v59, v35, s[0:1]
	v_rsq_f32_e32 v35, v35
	s_nop 0
	v_mul_f32_e32 v39, 0x45800000, v35
	v_cndmask_b32_e64 v86, v35, v39, s[0:1]
	v_mul_f32_e32 v35, 0x4b800000, v58
	v_cndmask_b32_e32 v35, v58, v35, vcc
	v_rsq_f32_e32 v35, v35
	v_pk_mul_f32 v[44:45], v[44:45], v[86:87] op_sel_hi:[1,0]
	v_pk_mul_f32 v[46:47], v[46:47], v[86:87] op_sel_hi:[1,0]
	s_waitcnt vmcnt(14)
	v_pk_fma_f32 v[54:55], v[26:27], v[44:45], v[30:31]
	v_pk_mul_f32 v[44:45], v[66:67], v[86:87] op_sel_hi:[1,0]
	v_mul_f32_e32 v39, 0x45800000, v35
	s_waitcnt vmcnt(12)
	v_pk_fma_f32 v[52:53], v[16:17], v[44:45], v[20:21]
	v_pk_mul_f32 v[44:45], v[64:65], v[86:87] op_sel_hi:[1,0]
	v_cndmask_b32_e32 v58, v35, v39, vcc
	v_pk_fma_f32 v[50:51], v[18:19], v[44:45], v[22:23]
	v_pk_mul_f32 v[44:45], v[62:63], v[86:87] op_sel_hi:[1,0]
	v_pk_fma_f32 v[56:57], v[24:25], v[46:47], v[28:29]
	s_waitcnt vmcnt(10)
	v_pk_fma_f32 v[48:49], v[8:9], v[44:45], v[12:13]
	v_pk_mul_f32 v[44:45], v[68:69], v[86:87] op_sel_hi:[1,0]
	v_pk_mul_f32 v[42:43], v[42:43], v[86:87] op_sel_hi:[1,0]
	v_pk_fma_f32 v[46:47], v[10:11], v[44:45], v[14:15]
	v_pk_mul_f32 v[44:45], v[60:61], v[86:87] op_sel_hi:[1,0]
	v_pk_mul_f32 v[60:61], v[80:81], v[58:59] op_sel_hi:[1,0]
	s_waitcnt vmcnt(8)
	v_pk_fma_f32 v[44:45], v[0:1], v[44:45], v[4:5]
	v_pk_fma_f32 v[24:25], v[24:25], v[60:61], v[28:29]
	v_pk_mul_f32 v[28:29], v[82:83], v[58:59] op_sel_hi:[1,0]
	v_pk_fma_f32 v[42:43], v[2:3], v[42:43], v[6:7]
	v_pk_fma_f32 v[26:27], v[26:27], v[28:29], v[30:31]
	v_pk_mul_f32 v[28:29], v[78:79], v[58:59] op_sel_hi:[1,0]
	v_cmp_lt_i32_e32 vcc, s16, v38
	v_pk_fma_f32 v[16:17], v[16:17], v[28:29], v[20:21]
	v_pk_mul_f32 v[20:21], v[76:77], v[58:59] op_sel_hi:[1,0]
	s_nop 0
	v_pk_fma_f32 v[18:19], v[18:19], v[20:21], v[22:23]
	v_pk_mul_f32 v[20:21], v[74:75], v[58:59] op_sel_hi:[1,0]
	s_nop 0
	v_pk_fma_f32 v[8:9], v[8:9], v[20:21], v[12:13]
	v_pk_mul_f32 v[12:13], v[84:85], v[58:59] op_sel_hi:[1,0]
	s_nop 0
	v_pk_fma_f32 v[10:11], v[10:11], v[12:13], v[14:15]
	v_pk_mul_f32 v[12:13], v[72:73], v[58:59] op_sel_hi:[1,0]
	s_nop 0
	v_pk_fma_f32 v[0:1], v[0:1], v[12:13], v[4:5]
	v_pk_mul_f32 v[4:5], v[70:71], v[58:59] op_sel_hi:[1,0]
	s_nop 0
	v_pk_fma_f32 v[2:3], v[2:3], v[4:5], v[6:7]
	s_waitcnt vmcnt(0)
	v_mov_b64_e32 v[4:5], v[210:211]
	v_mov_b64_e32 v[6:7], v[212:213]
	v_mov_b64_e32 v[12:13], v[214:215]
	v_mov_b64_e32 v[14:15], v[216:217]
	v_mov_b64_e32 v[20:21], v[218:219]
	v_mov_b64_e32 v[22:23], v[220:221]
	v_mov_b64_e32 v[28:29], v[222:223]
	v_mov_b64_e32 v[30:31], v[224:225]
	v_mov_b64_e32 v[58:59], v[226:227]
	v_mov_b64_e32 v[60:61], v[228:229]
	v_mov_b64_e32 v[62:63], v[230:231]
	v_mov_b64_e32 v[64:65], v[232:233]
	v_mov_b64_e32 v[66:67], v[234:235]
	v_mov_b64_e32 v[68:69], v[236:237]
	v_mov_b64_e32 v[70:71], v[238:239]
	v_mov_b64_e32 v[72:73], v[240:241]
	v_cvt_pk_bf16_f32 v40, v56, v57
	v_cvt_pk_bf16_f32 v41, v54, v55
	global_store_dwordx2 v[36:37], v[40:41], off

	v_pk_add_f32 v[12:13], v[12:13], 1.0 op_sel_hi:[1,0]
	v_pk_add_f32 v[14:15], v[14:15], 1.0 op_sel_hi:[1,0]
	v_pk_fma_f32 v[40:41], v[12:13], v[56:57], v[4:5]
	v_pk_fma_f32 v[54:55], v[14:15], v[54:55], v[6:7]
	v_cvt_pk_bf16_f32 v40, v40, v41
	v_cvt_pk_bf16_f32 v41, v54, v55
	v_mov_b64_e32 v[54:55], s[62:63]
	v_mad_i64_i32 v[38:39], s[0:1], v38, s36, v[54:55]
	v_lshl_add_u64 v[38:39], v[38:39], 0, v[136:137]
	global_store_dwordx2 v[38:39], v[40:41], off
	v_cvt_pk_bf16_f32 v40, v52, v53
	v_cvt_pk_bf16_f32 v41, v50, v51

	v_pk_add_f32 v[28:29], v[28:29], 1.0 op_sel_hi:[1,0]
	v_pk_add_f32 v[30:31], v[30:31], 1.0 op_sel_hi:[1,0]
	global_store_dwordx2 v[36:37], v[40:41], off offset:512
	v_pk_fma_f32 v[40:41], v[28:29], v[52:53], v[20:21]
	v_pk_fma_f32 v[50:51], v[30:31], v[50:51], v[22:23]
	v_cvt_pk_bf16_f32 v40, v40, v41
	v_cvt_pk_bf16_f32 v41, v50, v51
	global_store_dwordx2 v[38:39], v[40:41], off offset:512
	v_cvt_pk_bf16_f32 v40, v48, v49
	v_cvt_pk_bf16_f32 v41, v46, v47
	global_store_dwordx2 v[36:37], v[40:41], off offset:1024

	v_pk_add_f32 v[40:41], v[62:63], 1.0 op_sel_hi:[1,0]
	v_pk_add_f32 v[50:51], v[64:65], 1.0 op_sel_hi:[1,0]
	v_pk_fma_f32 v[48:49], v[40:41], v[48:49], v[58:59]
	v_pk_fma_f32 v[46:47], v[50:51], v[46:47], v[60:61]
	v_cvt_pk_bf16_f32 v48, v48, v49
	v_cvt_pk_bf16_f32 v49, v46, v47
	v_cvt_pk_bf16_f32 v46, v44, v45
	v_cvt_pk_bf16_f32 v47, v42, v43
	global_store_dwordx2 v[38:39], v[48:49], off offset:1024
	global_store_dwordx2 v[36:37], v[46:47], off offset:1536

	v_pk_add_f32 v[36:37], v[70:71], 1.0 op_sel_hi:[1,0]
	v_pk_add_f32 v[46:47], v[72:73], 1.0 op_sel_hi:[1,0]
	v_pk_fma_f32 v[44:45], v[36:37], v[44:45], v[66:67]
	v_pk_fma_f32 v[42:43], v[46:47], v[42:43], v[68:69]
	v_pk_fma_f32 v[4:5], v[12:13], v[24:25], v[4:5]
	v_pk_fma_f32 v[6:7], v[14:15], v[26:27], v[6:7]
	v_cvt_pk_bf16_f32 v44, v44, v45
	v_cvt_pk_bf16_f32 v45, v42, v43
	v_cvt_pk_bf16_f32 v4, v4, v5
	v_cvt_pk_bf16_f32 v5, v6, v7
	v_mad_i64_i32 v[6:7], s[0:1], v34, s36, v[54:55]
	global_store_dwordx2 v[38:39], v[44:45], off offset:1536
	v_cvt_pk_bf16_f32 v38, v24, v25
	v_cvt_pk_bf16_f32 v39, v26, v27
	v_lshl_add_u64 v[6:7], v[6:7], 0, v[136:137]
	global_store_dwordx2 v[32:33], v[38:39], off
	global_store_dwordx2 v[6:7], v[4:5], off
	v_cvt_pk_bf16_f32 v4, v16, v17
	v_cvt_pk_bf16_f32 v5, v18, v19
	global_store_dwordx2 v[32:33], v[4:5], off offset:512
	v_pk_fma_f32 v[4:5], v[28:29], v[16:17], v[20:21]
	v_pk_fma_f32 v[12:13], v[30:31], v[18:19], v[22:23]
	v_cvt_pk_bf16_f32 v4, v4, v5
	v_cvt_pk_bf16_f32 v5, v12, v13
	global_store_dwordx2 v[6:7], v[4:5], off offset:512
	v_cvt_pk_bf16_f32 v4, v8, v9
	v_cvt_pk_bf16_f32 v5, v10, v11
	global_store_dwordx2 v[32:33], v[4:5], off offset:1024
	v_pk_fma_f32 v[4:5], v[40:41], v[8:9], v[58:59]
	v_pk_fma_f32 v[8:9], v[50:51], v[10:11], v[60:61]
	v_cvt_pk_bf16_f32 v4, v4, v5
	v_cvt_pk_bf16_f32 v5, v8, v9
	global_store_dwordx2 v[6:7], v[4:5], off offset:1024
	v_cvt_pk_bf16_f32 v4, v0, v1
	v_cvt_pk_bf16_f32 v5, v2, v3
	v_pk_fma_f32 v[0:1], v[36:37], v[0:1], v[66:67]
	v_pk_fma_f32 v[2:3], v[46:47], v[2:3], v[68:69]
	v_cvt_pk_bf16_f32 v0, v0, v1
	v_cvt_pk_bf16_f32 v1, v2, v3
	global_store_dwordx2 v[32:33], v[4:5], off offset:1536
	global_store_dwordx2 v[6:7], v[0:1], off offset:1536
	s_cbranch_scc0 .LBB0_123

.LBB0_157:
	v_mov_b32_e32 v0, v139
	v_cmp_lt_i32_e32 vcc, v179, v178
	v_ashrrev_i32_e32 v1, 5, v0
	v_and_b32_e32 v1, -2, v1
	v_add_u32_e32 v38, s9, v1
	v_lshlrev_b32_e32 v0, 2, v0
	v_ashrrev_i32_e32 v39, 31, v38
	v_and_b32_e32 v2, 0xfc, v0
	v_lshlrev_b64 v[0:1], 12, v[38:39]
	v_lshl_add_u64 v[0:1], s[46:47], 0, v[0:1]
	v_lshlrev_b32_e32 v136, 1, v2
	v_lshl_add_u64 v[36:37], v[0:1], 0, v[136:137]
	global_load_dwordx2 v[42:43], v[36:37], off offset:2048
	global_load_dwordx2 v[44:45], v[36:37], off offset:2560
	global_load_dwordx2 v[46:47], v[36:37], off offset:3072
	global_load_dwordx2 v[48:49], v[36:37], off offset:3584
	s_waitcnt vmcnt(12)
	v_add_u32_e32 v34, 1, v38
	v_ashrrev_i32_e32 v35, 31, v34
	v_lshlrev_b64 v[0:1], 12, v[34:35]
	v_lshl_add_u64 v[0:1], s[46:47], 0, v[0:1]
	v_lshl_add_u64 v[32:33], v[0:1], 0, v[136:137]
	global_load_dwordx2 v[50:51], v[32:33], off offset:2048
	global_load_dwordx2 v[52:53], v[32:33], off offset:2560
	global_load_dwordx2 v[54:55], v[32:33], off offset:3072
	global_load_dwordx2 v[56:57], v[32:33], off offset:3584
	v_cndmask_b32_e32 v35, v176, v179, vcc
	v_cmp_lt_i32_e32 vcc, v180, v178
	v_lshlrev_b32_e32 v35, 2, v35
	v_lshlrev_b32_e32 v40, 2, v2
	v_cndmask_b32_e32 v39, v176, v180, vcc
	v_cmp_lt_i32_e32 vcc, v181, v178
	v_lshlrev_b32_e32 v39, 2, v39
	global_load_dwordx4 v[24:27], v40, s[4:5]
	global_load_dwordx4 v[28:31], v40, s[6:7]
	global_load_dwordx4 v[16:19], v40, s[4:5] offset:1024
	global_load_dwordx4 v[20:23], v40, s[6:7] offset:1024
	global_load_dwordx4 v[8:11], v40, s[4:5] offset:2048
	global_load_dwordx4 v[12:15], v40, s[6:7] offset:2048
	global_load_dwordx4 v[0:3], v40, s[4:5] offset:3072
	global_load_dwordx4 v[4:7], v40, s[6:7] offset:3072
	v_mov_b32_e32 v252, v40
	v_mov_b32_e32 v253, v137
	v_cmp_lt_i32_e64 s[98:99], s13, v38
	v_add_u32_e32 v202, 0xfffff000, v38
	v_lshrrev_b32_e32 v202, 12, v202
	v_add_u32_e32 v202, 1, v202
	v_cndmask_b32_e64 v202, 0, v202, s[98:99]
	v_mov_b32_e32 v203, v137
	v_lshl_add_u64 v[202:203], v[202:203], 0, s[2:3]
	v_mov_b64_e32 v[204:205], s[56:57]
	v_mad_u64_u32 v[204:205], s[98:99], v202, s12, v[204:205]
	v_mad_i32_i24 v205, v203, s12, v205
	v_lshl_add_u64 v[202:203], v[204:205], 0, v[252:253]
	v_add_co_u32_e64 v206, s[98:99], s11, v202
	v_lshl_add_u64 v[208:209], v[202:203], 0, s[18:19]
	s_nop 1
	v_addc_co_u32_e64 v207, s[98:99], 0, v203, s[98:99]
	v_lshl_add_u64 v[252:253], v[202:203], 0, s[14:15]
	global_load_dwordx4 v[210:213], v[206:207], off offset:-4096
	global_load_dwordx4 v[214:217], v[206:207], off
	global_load_dwordx4 v[218:221], v[252:253], off offset:1024
	global_load_dwordx4 v[222:225], v[208:209], off offset:1024
	global_load_dwordx4 v[226:229], v[252:253], off offset:2048
	global_load_dwordx4 v[230:233], v[208:209], off offset:2048
	global_load_dwordx4 v[234:237], v[252:253], off offset:3072
	global_load_dwordx4 v[238:241], v[208:209], off offset:3072
	v_cndmask_b32_e32 v58, v176, v181, vcc
	v_cmp_lt_i32_e32 vcc, v182, v178
	v_lshlrev_b32_e32 v86, 2, v58
	v_mov_b32_e32 v41, v137
	v_cndmask_b32_e32 v58, v176, v182, vcc
	v_cmp_lt_i32_e32 vcc, v183, v178
	v_lshlrev_b32_e32 v87, 2, v58
	s_add_i32 s10, s10, s20
	v_cndmask_b32_e32 v58, v176, v183, vcc
	v_cmp_lt_i32_e32 vcc, v184, v178
	v_lshlrev_b32_e32 v88, 2, v58
	s_add_i32 s9, s9, s8
	v_cndmask_b32_e32 v58, v176, v184, vcc
	v_lshlrev_b32_e32 v89, 2, v58
	s_cmpk_gt_i32 s10, 0x5ff
	s_waitcnt vmcnt(23)
	v_lshlrev_b32_e32 v68, 16, v42
	s_waitcnt vmcnt(22)
	v_lshlrev_b32_e32 v66, 16, v44
	s_waitcnt vmcnt(21)
	v_lshlrev_b32_e32 v62, 16, v46
	s_waitcnt vmcnt(20)
	v_lshlrev_b32_e32 v60, 16, v48
	v_and_b32_e32 v61, 0xffff0000, v48
	v_and_b32_e32 v63, 0xffff0000, v46
	v_lshlrev_b32_e32 v58, 16, v49
	v_and_b32_e32 v59, 0xffff0000, v49
	v_lshlrev_b32_e32 v48, 16, v47
	v_and_b32_e32 v49, 0xffff0000, v47
	v_mov_b32_e32 v46, v62
	v_mov_b32_e32 v47, v60
	v_mov_b32_e32 v64, v63
	v_mov_b32_e32 v65, v61
	v_pk_add_f32 v[46:47], v[46:47], v[64:65]
	v_mov_b32_e32 v64, v48
	v_mov_b32_e32 v65, v58
	v_pk_add_f32 v[46:47], v[46:47], v[64:65]
	v_mov_b32_e32 v64, v49
	v_mov_b32_e32 v65, v59
	v_and_b32_e32 v67, 0xffff0000, v44
	v_and_b32_e32 v69, 0xffff0000, v42
	v_pk_add_f32 v[46:47], v[46:47], v[64:65]
	v_lshlrev_b32_e32 v64, 16, v45
	v_and_b32_e32 v65, 0xffff0000, v45
	v_lshlrev_b32_e32 v44, 16, v43
	v_and_b32_e32 v45, 0xffff0000, v43
	v_mov_b32_e32 v42, v68
	v_mov_b32_e32 v43, v66
	v_mov_b32_e32 v70, v69
	v_mov_b32_e32 v71, v67
	v_pk_add_f32 v[42:43], v[42:43], v[70:71]
	v_mov_b32_e32 v70, v44
	v_mov_b32_e32 v71, v64
	v_pk_add_f32 v[42:43], v[42:43], v[70:71]
	v_mov_b32_e32 v70, v45
	v_mov_b32_e32 v71, v65
	s_waitcnt vmcnt(16)
	v_lshlrev_b32_e32 v72, 16, v56
	v_and_b32_e32 v73, 0xffff0000, v56
	v_lshlrev_b32_e32 v74, 16, v54
	v_and_b32_e32 v75, 0xffff0000, v54
	v_pk_add_f32 v[42:43], v[42:43], v[70:71]
	v_lshlrev_b32_e32 v70, 16, v57
	v_and_b32_e32 v71, 0xffff0000, v57
	v_lshlrev_b32_e32 v56, 16, v55
	v_and_b32_e32 v57, 0xffff0000, v55
	v_mov_b32_e32 v54, v74
	v_mov_b32_e32 v55, v72
	v_mov_b32_e32 v76, v75
	v_mov_b32_e32 v77, v73
	v_pk_add_f32 v[54:55], v[54:55], v[76:77]
	v_mov_b32_e32 v76, v56
	v_mov_b32_e32 v77, v70
	v_pk_add_f32 v[54:55], v[54:55], v[76:77]
	v_mov_b32_e32 v76, v57
	v_mov_b32_e32 v77, v71
	v_lshlrev_b32_e32 v78, 16, v52
	v_and_b32_e32 v79, 0xffff0000, v52
	v_lshlrev_b32_e32 v80, 16, v50
	v_and_b32_e32 v81, 0xffff0000, v50
	v_pk_add_f32 v[54:55], v[54:55], v[76:77]
	v_lshlrev_b32_e32 v76, 16, v53
	v_and_b32_e32 v77, 0xffff0000, v53
	v_lshlrev_b32_e32 v52, 16, v51
	v_and_b32_e32 v53, 0xffff0000, v51
	v_mov_b32_e32 v50, v80
	v_mov_b32_e32 v51, v78
	v_mov_b32_e32 v82, v81
	v_mov_b32_e32 v83, v79
	v_pk_add_f32 v[50:51], v[50:51], v[82:83]
	v_mov_b32_e32 v82, v52
	v_mov_b32_e32 v83, v76
	v_pk_add_f32 v[50:51], v[50:51], v[82:83]
	v_mov_b32_e32 v82, v53
	v_mov_b32_e32 v83, v77
	v_pk_add_f32 v[50:51], v[50:51], v[82:83]
	v_add_f32_e32 v42, 0, v42
	v_add_f32_e32 v50, 0, v50
	v_add_f32_e32 v42, v42, v43
	v_add_f32_e32 v50, v50, v51
	v_add_f32_e32 v42, v42, v46
	v_add_f32_e32 v50, v50, v54
	v_add_f32_e32 v42, v42, v47
	v_add_f32_e32 v50, v50, v55
	ds_bpermute_b32 v43, v35, v42
	ds_bpermute_b32 v51, v35, v50
	s_waitcnt lgkmcnt(1)
	v_add_f32_e32 v42, v42, v43
	s_waitcnt lgkmcnt(0)
	v_add_f32_e32 v50, v50, v51
	ds_bpermute_b32 v43, v39, v42
	ds_bpermute_b32 v51, v39, v50
	s_waitcnt lgkmcnt(1)
	v_add_f32_e32 v42, v42, v43
	s_waitcnt lgkmcnt(0)
	v_add_f32_e32 v50, v50, v51
	ds_bpermute_b32 v43, v86, v42
	ds_bpermute_b32 v51, v86, v50
	s_waitcnt lgkmcnt(1)
	v_add_f32_e32 v42, v42, v43
	s_waitcnt lgkmcnt(0)
	v_add_f32_e32 v50, v50, v51
	ds_bpermute_b32 v43, v87, v42
	ds_bpermute_b32 v51, v87, v50
	s_waitcnt lgkmcnt(1)
	v_add_f32_e32 v42, v42, v43
	s_waitcnt lgkmcnt(0)
	v_add_f32_e32 v50, v50, v51
	ds_bpermute_b32 v43, v88, v42
	ds_bpermute_b32 v51, v88, v50
	s_waitcnt lgkmcnt(1)
	v_add_f32_e32 v42, v42, v43
	s_waitcnt lgkmcnt(0)
	v_add_f32_e32 v50, v50, v51
	ds_bpermute_b32 v43, v89, v42
	ds_bpermute_b32 v51, v89, v50
	s_waitcnt lgkmcnt(1)
	v_add_f32_e32 v42, v42, v43
	s_waitcnt lgkmcnt(0)
	v_add_f32_e32 v50, v50, v51
	v_mul_f32_e32 v42, 0x3a800000, v42
	v_mul_f32_e32 v50, 0x3a800000, v50
	v_pk_add_f32 v[46:47], v[68:69], v[42:43] op_sel_hi:[1,0] neg_lo:[0,1] neg_hi:[0,1]
	v_pk_add_f32 v[80:81], v[80:81], v[50:51] op_sel_hi:[1,0] neg_lo:[0,1] neg_hi:[0,1]
	v_mov_b32_e32 v83, v47
	v_mov_b32_e32 v82, v81
	v_mov_b32_e32 v54, v80
	v_mov_b32_e32 v55, v46
	v_pk_mul_f32 v[82:83], v[82:83], v[82:83]
	v_pk_add_f32 v[44:45], v[44:45], v[42:43] op_sel_hi:[1,0] neg_lo:[0,1] neg_hi:[0,1]
	v_pk_fma_f32 v[54:55], v[54:55], v[54:55], v[82:83]
	v_pk_add_f32 v[82:83], v[52:53], v[50:51] op_sel_hi:[1,0] neg_lo:[0,1] neg_hi:[0,1]
	v_mov_b32_e32 v53, v44
	v_mov_b32_e32 v52, v82
	v_pk_add_f32 v[66:67], v[66:67], v[42:43] op_sel_hi:[1,0] neg_lo:[0,1] neg_hi:[0,1]
	v_pk_add_f32 v[78:79], v[78:79], v[50:51] op_sel_hi:[1,0] neg_lo:[0,1] neg_hi:[0,1]
	v_pk_fma_f32 v[52:53], v[52:53], v[52:53], v[54:55]
	v_mov_b32_e32 v54, v83
	v_mov_b32_e32 v55, v45
	v_pk_fma_f32 v[52:53], v[54:55], v[54:55], v[52:53]
	v_mov_b32_e32 v54, v78
	v_mov_b32_e32 v55, v66
	v_pk_add_f32 v[64:65], v[64:65], v[42:43] op_sel_hi:[1,0] neg_lo:[0,1] neg_hi:[0,1]
	v_pk_add_f32 v[76:77], v[76:77], v[50:51] op_sel_hi:[1,0] neg_lo:[0,1] neg_hi:[0,1]
	v_pk_fma_f32 v[52:53], v[54:55], v[54:55], v[52:53]
	v_mov_b32_e32 v54, v79
	v_mov_b32_e32 v55, v67
	v_pk_fma_f32 v[52:53], v[54:55], v[54:55], v[52:53]
	v_mov_b32_e32 v54, v76
	v_mov_b32_e32 v55, v64
	v_pk_add_f32 v[62:63], v[62:63], v[42:43] op_sel_hi:[1,0] neg_lo:[0,1] neg_hi:[0,1]
	v_pk_add_f32 v[74:75], v[74:75], v[50:51] op_sel_hi:[1,0] neg_lo:[0,1] neg_hi:[0,1]
	v_pk_fma_f32 v[52:53], v[54:55], v[54:55], v[52:53]
	v_mov_b32_e32 v54, v77
	v_mov_b32_e32 v55, v65
	v_pk_fma_f32 v[52:53], v[54:55], v[54:55], v[52:53]
	v_mov_b32_e32 v54, v74
	v_mov_b32_e32 v55, v62
	v_pk_add_f32 v[68:69], v[48:49], v[42:43] op_sel_hi:[1,0] neg_lo:[0,1] neg_hi:[0,1]
	v_pk_add_f32 v[84:85], v[56:57], v[50:51] op_sel_hi:[1,0] neg_lo:[0,1] neg_hi:[0,1]
	v_pk_fma_f32 v[52:53], v[54:55], v[54:55], v[52:53]
	v_mov_b32_e32 v54, v75
	v_mov_b32_e32 v55, v63
	v_pk_add_f32 v[60:61], v[60:61], v[42:43] op_sel_hi:[1,0] neg_lo:[0,1] neg_hi:[0,1]
	v_pk_add_f32 v[72:73], v[72:73], v[50:51] op_sel_hi:[1,0] neg_lo:[0,1] neg_hi:[0,1]
	v_pk_fma_f32 v[52:53], v[54:55], v[54:55], v[52:53]
	v_mov_b32_e32 v54, v84
	v_mov_b32_e32 v55, v68
	v_pk_mul_f32 v[48:49], v[60:61], v[60:61]
	v_pk_mul_f32 v[56:57], v[72:73], v[72:73]
	v_pk_fma_f32 v[52:53], v[54:55], v[54:55], v[52:53]
	v_mov_b32_e32 v54, v85
	v_mov_b32_e32 v55, v69
	v_pk_add_f32 v[42:43], v[58:59], v[42:43] op_sel_hi:[1,0] neg_lo:[0,1] neg_hi:[0,1]
	v_pk_fma_f32 v[52:53], v[54:55], v[54:55], v[52:53]
	v_mov_b32_e32 v54, v56
	v_mov_b32_e32 v55, v48
	v_pk_add_f32 v[70:71], v[70:71], v[50:51] op_sel_hi:[1,0] neg_lo:[0,1] neg_hi:[0,1]
	v_pk_mul_f32 v[58:59], v[42:43], v[42:43]
	v_pk_add_f32 v[52:53], v[54:55], v[52:53]
	v_pk_mul_f32 v[50:51], v[70:71], v[70:71]
	v_mov_b32_e32 v48, v57
	v_pk_add_f32 v[48:49], v[48:49], v[52:53]
	v_mov_b32_e32 v52, v50
	v_mov_b32_e32 v53, v58
	v_pk_add_f32 v[48:49], v[52:53], v[48:49]
	v_mov_b32_e32 v58, v51
	v_pk_add_f32 v[48:49], v[58:59], v[48:49]
	v_mov_b32_e32 v50, v48
	v_mov_b32_e32 v51, v49
	s_nop 1
	v_permlane32_swap_b32_e32 v50, v48
	v_permlane32_swap_b32_e32 v51, v49
	v_pk_add_f32 v[48:49], v[48:49], v[50:51]
	v_mov_b32_e32 v50, v48
	v_mov_b32_e32 v51, v49
	s_nop 1
	v_permlane16_swap_b32_e32 v50, v48
	v_permlane16_swap_b32_e32 v51, v49
	v_pk_add_f32 v[48:49], v[48:49], v[50:51]
	s_nop 1
	v_add_f32_dpp v48, v48, v48 row_ror:8 row_mask:0xf bank_mask:0xf
	v_add_f32_dpp v49, v49, v49 row_ror:8 row_mask:0xf bank_mask:0xf
	s_nop 0
	v_add_f32_dpp v48, v48, v48 row_ror:4 row_mask:0xf bank_mask:0xf
	v_add_f32_dpp v49, v49, v49 row_ror:4 row_mask:0xf bank_mask:0xf
	s_nop 0
	v_add_f32_dpp v48, v48, v48 row_ror:2 row_mask:0xf bank_mask:0xf
	v_add_f32_dpp v49, v49, v49 row_ror:2 row_mask:0xf bank_mask:0xf
	s_nop 0
	v_add_f32_dpp v48, v48, v48 row_ror:1 row_mask:0xf bank_mask:0xf
	v_add_f32_dpp v49, v49, v49 row_ror:1 row_mask:0xf bank_mask:0xf
	s_nop 0
	v_pk_fma_f32 v[58:59], v[48:49], s[16:17], v[138:139] op_sel_hi:[1,0,0]
	s_nop 0
	v_mul_f32_e32 v35, 0x4b800000, v59
	v_cmp_gt_f32_e64 s[0:1], s33, v59
	v_cmp_gt_f32_e32 vcc, s33, v58
	s_nop 0
	v_cndmask_b32_e64 v35, v59, v35, s[0:1]
	v_rsq_f32_e32 v35, v35
	s_nop 0
	v_mul_f32_e32 v39, 0x45800000, v35
	v_cndmask_b32_e64 v86, v35, v39, s[0:1]
	v_mul_f32_e32 v35, 0x4b800000, v58
	v_cndmask_b32_e32 v35, v58, v35, vcc
	v_rsq_f32_e32 v35, v35
	v_pk_mul_f32 v[44:45], v[44:45], v[86:87] op_sel_hi:[1,0]
	v_pk_mul_f32 v[46:47], v[46:47], v[86:87] op_sel_hi:[1,0]
	s_waitcnt vmcnt(14)
	v_pk_fma_f32 v[54:55], v[26:27], v[44:45], v[30:31]
	v_pk_mul_f32 v[44:45], v[66:67], v[86:87] op_sel_hi:[1,0]
	v_mul_f32_e32 v39, 0x45800000, v35
	s_waitcnt vmcnt(12)
	v_pk_fma_f32 v[52:53], v[16:17], v[44:45], v[20:21]
	v_pk_mul_f32 v[44:45], v[64:65], v[86:87] op_sel_hi:[1,0]
	v_cndmask_b32_e32 v58, v35, v39, vcc
	v_pk_fma_f32 v[50:51], v[18:19], v[44:45], v[22:23]
	v_pk_mul_f32 v[44:45], v[62:63], v[86:87] op_sel_hi:[1,0]
	v_pk_fma_f32 v[56:57], v[24:25], v[46:47], v[28:29]
	s_waitcnt vmcnt(10)
	v_pk_fma_f32 v[48:49], v[8:9], v[44:45], v[12:13]
	v_pk_mul_f32 v[44:45], v[68:69], v[86:87] op_sel_hi:[1,0]
	v_pk_mul_f32 v[42:43], v[42:43], v[86:87] op_sel_hi:[1,0]
	v_pk_fma_f32 v[46:47], v[10:11], v[44:45], v[14:15]
	v_pk_mul_f32 v[44:45], v[60:61], v[86:87] op_sel_hi:[1,0]
	v_pk_mul_f32 v[60:61], v[80:81], v[58:59] op_sel_hi:[1,0]
	s_waitcnt vmcnt(8)
	v_pk_fma_f32 v[44:45], v[0:1], v[44:45], v[4:5]
	v_pk_fma_f32 v[24:25], v[24:25], v[60:61], v[28:29]
	v_pk_mul_f32 v[28:29], v[82:83], v[58:59] op_sel_hi:[1,0]
	v_pk_fma_f32 v[42:43], v[2:3], v[42:43], v[6:7]
	v_pk_fma_f32 v[26:27], v[26:27], v[28:29], v[30:31]
	v_pk_mul_f32 v[28:29], v[78:79], v[58:59] op_sel_hi:[1,0]
	v_cmp_lt_i32_e32 vcc, s13, v38
	v_pk_fma_f32 v[16:17], v[16:17], v[28:29], v[20:21]
	v_pk_mul_f32 v[20:21], v[76:77], v[58:59] op_sel_hi:[1,0]
	s_nop 0
	v_pk_fma_f32 v[18:19], v[18:19], v[20:21], v[22:23]
	v_pk_mul_f32 v[20:21], v[74:75], v[58:59] op_sel_hi:[1,0]
	s_nop 0
	v_pk_fma_f32 v[8:9], v[8:9], v[20:21], v[12:13]
	v_pk_mul_f32 v[12:13], v[84:85], v[58:59] op_sel_hi:[1,0]
	s_nop 0
	v_pk_fma_f32 v[10:11], v[10:11], v[12:13], v[14:15]
	v_pk_mul_f32 v[12:13], v[72:73], v[58:59] op_sel_hi:[1,0]
	s_nop 0
	v_pk_fma_f32 v[0:1], v[0:1], v[12:13], v[4:5]
	v_pk_mul_f32 v[4:5], v[70:71], v[58:59] op_sel_hi:[1,0]
	s_nop 0
	v_pk_fma_f32 v[2:3], v[2:3], v[4:5], v[6:7]
	s_waitcnt vmcnt(0)
	v_mov_b64_e32 v[4:5], v[210:211]
	v_mov_b64_e32 v[6:7], v[212:213]
	v_mov_b64_e32 v[12:13], v[214:215]
	v_mov_b64_e32 v[14:15], v[216:217]
	v_mov_b64_e32 v[20:21], v[218:219]
	v_mov_b64_e32 v[22:23], v[220:221]
	v_mov_b64_e32 v[28:29], v[222:223]
	v_mov_b64_e32 v[30:31], v[224:225]
	v_mov_b64_e32 v[58:59], v[226:227]
	v_mov_b64_e32 v[60:61], v[228:229]
	v_mov_b64_e32 v[62:63], v[230:231]
	v_mov_b64_e32 v[64:65], v[232:233]
	v_mov_b64_e32 v[66:67], v[234:235]
	v_mov_b64_e32 v[68:69], v[236:237]
	v_mov_b64_e32 v[70:71], v[238:239]
	v_mov_b64_e32 v[72:73], v[240:241]
	v_cvt_pk_bf16_f32 v40, v56, v57
	v_cvt_pk_bf16_f32 v41, v54, v55
	global_store_dwordx2 v[36:37], v[40:41], off

	v_pk_add_f32 v[12:13], v[12:13], 1.0 op_sel_hi:[1,0]
	v_pk_add_f32 v[14:15], v[14:15], 1.0 op_sel_hi:[1,0]
	v_pk_fma_f32 v[40:41], v[12:13], v[56:57], v[4:5]
	v_pk_fma_f32 v[54:55], v[14:15], v[54:55], v[6:7]
	v_cvt_pk_bf16_f32 v40, v40, v41
	v_cvt_pk_bf16_f32 v41, v54, v55
	v_mov_b64_e32 v[54:55], s[62:63]
	v_mad_i64_i32 v[38:39], s[0:1], v38, s36, v[54:55]
	v_lshl_add_u64 v[38:39], v[38:39], 0, v[136:137]
	global_store_dwordx2 v[38:39], v[40:41], off
	v_cvt_pk_bf16_f32 v40, v52, v53
	v_cvt_pk_bf16_f32 v41, v50, v51

	v_pk_add_f32 v[28:29], v[28:29], 1.0 op_sel_hi:[1,0]
	v_pk_add_f32 v[30:31], v[30:31], 1.0 op_sel_hi:[1,0]
	global_store_dwordx2 v[36:37], v[40:41], off offset:512
	v_pk_fma_f32 v[40:41], v[28:29], v[52:53], v[20:21]
	v_pk_fma_f32 v[50:51], v[30:31], v[50:51], v[22:23]
	v_cvt_pk_bf16_f32 v40, v40, v41
	v_cvt_pk_bf16_f32 v41, v50, v51
	global_store_dwordx2 v[38:39], v[40:41], off offset:512
	v_cvt_pk_bf16_f32 v40, v48, v49
	v_cvt_pk_bf16_f32 v41, v46, v47
	global_store_dwordx2 v[36:37], v[40:41], off offset:1024

	v_pk_add_f32 v[40:41], v[62:63], 1.0 op_sel_hi:[1,0]
	v_pk_add_f32 v[50:51], v[64:65], 1.0 op_sel_hi:[1,0]
	v_pk_fma_f32 v[48:49], v[40:41], v[48:49], v[58:59]
	v_pk_fma_f32 v[46:47], v[50:51], v[46:47], v[60:61]
	v_cvt_pk_bf16_f32 v48, v48, v49
	v_cvt_pk_bf16_f32 v49, v46, v47
	v_cvt_pk_bf16_f32 v46, v44, v45
	v_cvt_pk_bf16_f32 v47, v42, v43
	global_store_dwordx2 v[38:39], v[48:49], off offset:1024
	global_store_dwordx2 v[36:37], v[46:47], off offset:1536

	v_pk_add_f32 v[36:37], v[70:71], 1.0 op_sel_hi:[1,0]
	v_pk_add_f32 v[46:47], v[72:73], 1.0 op_sel_hi:[1,0]
	v_pk_fma_f32 v[44:45], v[36:37], v[44:45], v[66:67]
	v_pk_fma_f32 v[42:43], v[46:47], v[42:43], v[68:69]
	v_pk_fma_f32 v[4:5], v[12:13], v[24:25], v[4:5]
	v_pk_fma_f32 v[6:7], v[14:15], v[26:27], v[6:7]
	v_cvt_pk_bf16_f32 v44, v44, v45
	v_cvt_pk_bf16_f32 v45, v42, v43
	v_cvt_pk_bf16_f32 v4, v4, v5
	v_cvt_pk_bf16_f32 v5, v6, v7
	v_mad_i64_i32 v[6:7], s[0:1], v34, s36, v[54:55]
	global_store_dwordx2 v[38:39], v[44:45], off offset:1536
	v_cvt_pk_bf16_f32 v38, v24, v25
	v_cvt_pk_bf16_f32 v39, v26, v27
	v_lshl_add_u64 v[6:7], v[6:7], 0, v[136:137]
	global_store_dwordx2 v[32:33], v[38:39], off
	global_store_dwordx2 v[6:7], v[4:5], off
	v_cvt_pk_bf16_f32 v4, v16, v17
	v_cvt_pk_bf16_f32 v5, v18, v19
	global_store_dwordx2 v[32:33], v[4:5], off offset:512
	v_pk_fma_f32 v[4:5], v[28:29], v[16:17], v[20:21]
	v_pk_fma_f32 v[12:13], v[30:31], v[18:19], v[22:23]
	v_cvt_pk_bf16_f32 v4, v4, v5
	v_cvt_pk_bf16_f32 v5, v12, v13
	global_store_dwordx2 v[6:7], v[4:5], off offset:512
	v_cvt_pk_bf16_f32 v4, v8, v9
	v_cvt_pk_bf16_f32 v5, v10, v11
	global_store_dwordx2 v[32:33], v[4:5], off offset:1024
	v_pk_fma_f32 v[4:5], v[40:41], v[8:9], v[58:59]
	v_pk_fma_f32 v[8:9], v[50:51], v[10:11], v[60:61]
	v_cvt_pk_bf16_f32 v4, v4, v5
	v_cvt_pk_bf16_f32 v5, v8, v9
	global_store_dwordx2 v[6:7], v[4:5], off offset:1024
	v_cvt_pk_bf16_f32 v4, v0, v1
	v_cvt_pk_bf16_f32 v5, v2, v3
	v_pk_fma_f32 v[0:1], v[36:37], v[0:1], v[66:67]
	v_pk_fma_f32 v[2:3], v[46:47], v[2:3], v[68:69]
	v_cvt_pk_bf16_f32 v0, v0, v1
	v_cvt_pk_bf16_f32 v1, v2, v3
	global_store_dwordx2 v[32:33], v[4:5], off offset:1536
	global_store_dwordx2 v[6:7], v[0:1], off offset:1536
	s_cbranch_scc0 .LBB0_157

.LBB0_1056:
	v_mov_b32_e32 v0, v139
	v_cmp_lt_i32_e32 vcc, v179, v178
	v_ashrrev_i32_e32 v1, 5, v0
	v_and_b32_e32 v1, -2, v1
	v_add_u32_e32 v38, s11, v1
	v_lshlrev_b32_e32 v0, 2, v0
	v_ashrrev_i32_e32 v39, 31, v38
	s_waitcnt lgkmcnt(0)
	v_and_b32_e32 v2, 0xfc, v0
	v_lshlrev_b64 v[0:1], 12, v[38:39]
	v_lshl_add_u64 v[0:1], s[46:47], 0, v[0:1]
	v_lshlrev_b32_e32 v136, 1, v2
	v_lshl_add_u64 v[36:37], v[0:1], 0, v[136:137]
	global_load_dwordx2 v[42:43], v[36:37], off offset:2048
	global_load_dwordx2 v[44:45], v[36:37], off offset:2560
	global_load_dwordx2 v[46:47], v[36:37], off offset:3072
	global_load_dwordx2 v[48:49], v[36:37], off offset:3584
	s_waitcnt vmcnt(12)
	v_add_u32_e32 v34, 1, v38
	v_ashrrev_i32_e32 v35, 31, v34
	v_lshlrev_b64 v[0:1], 12, v[34:35]
	v_lshl_add_u64 v[0:1], s[46:47], 0, v[0:1]
	v_lshl_add_u64 v[32:33], v[0:1], 0, v[136:137]
	global_load_dwordx2 v[50:51], v[32:33], off offset:2048
	global_load_dwordx2 v[52:53], v[32:33], off offset:2560
	global_load_dwordx2 v[54:55], v[32:33], off offset:3072
	global_load_dwordx2 v[56:57], v[32:33], off offset:3584
	v_cndmask_b32_e32 v35, v176, v179, vcc
	v_cmp_lt_i32_e32 vcc, v180, v178
	v_lshlrev_b32_e32 v35, 2, v35
	v_lshlrev_b32_e32 v40, 2, v2
	v_cndmask_b32_e32 v39, v176, v180, vcc
	v_cmp_lt_i32_e32 vcc, v181, v178
	v_lshlrev_b32_e32 v39, 2, v39
	global_load_dwordx4 v[24:27], v40, s[4:5]
	global_load_dwordx4 v[28:31], v40, s[6:7]
	global_load_dwordx4 v[16:19], v40, s[4:5] offset:1024
	global_load_dwordx4 v[20:23], v40, s[6:7] offset:1024
	global_load_dwordx4 v[8:11], v40, s[4:5] offset:2048
	global_load_dwordx4 v[12:15], v40, s[6:7] offset:2048
	global_load_dwordx4 v[0:3], v40, s[4:5] offset:3072
	global_load_dwordx4 v[4:7], v40, s[6:7] offset:3072
	v_mov_b32_e32 v252, v40
	v_mov_b32_e32 v253, v137
	v_cmp_lt_i32_e64 s[98:99], s17, v38
	v_add_u32_e32 v202, 0xfffff000, v38
	v_lshrrev_b32_e32 v202, 12, v202
	v_add_u32_e32 v202, 1, v202
	v_cndmask_b32_e64 v202, 0, v202, s[98:99]
	v_mov_b32_e32 v203, v137
	v_lshl_add_u64 v[202:203], v[202:203], 0, s[8:9]
	v_mov_b64_e32 v[204:205], s[56:57]
	v_mad_u64_u32 v[204:205], s[98:99], v202, s16, v[204:205]
	v_mad_i32_i24 v205, v203, s16, v205
	v_lshl_add_u64 v[252:253], v[204:205], 0, v[252:253]
	global_load_dwordx4 v[206:209], v[252:253], off
	v_add_co_u32_e64 v210, s[98:99], s13, v252
	v_lshl_add_u64 v[212:213], v[252:253], 0, s[18:19]
	s_nop 1
	v_addc_co_u32_e64 v211, s[98:99], 0, v253, s[98:99]
	global_load_dwordx4 v[214:217], v[210:211], off
	global_load_dwordx4 v[218:221], v[252:253], off offset:1024
	global_load_dwordx4 v[222:225], v[212:213], off offset:1024
	global_load_dwordx4 v[226:229], v[252:253], off offset:2048
	global_load_dwordx4 v[230:233], v[212:213], off offset:2048
	global_load_dwordx4 v[234:237], v[252:253], off offset:3072
	global_load_dwordx4 v[238:241], v[212:213], off offset:3072
	v_cndmask_b32_e32 v58, v176, v181, vcc
	v_cmp_lt_i32_e32 vcc, v182, v178
	v_lshlrev_b32_e32 v86, 2, v58
	v_mov_b32_e32 v41, v137
	v_cndmask_b32_e32 v58, v176, v182, vcc
	v_cmp_lt_i32_e32 vcc, v183, v178
	v_lshlrev_b32_e32 v87, 2, v58
	s_add_i32 s12, s12, s90
	v_cndmask_b32_e32 v58, v176, v183, vcc
	v_cmp_lt_i32_e32 vcc, v184, v178
	v_lshlrev_b32_e32 v88, 2, v58
	s_add_i32 s11, s11, s10
	v_cndmask_b32_e32 v58, v176, v184, vcc
	v_lshlrev_b32_e32 v89, 2, v58
	s_cmpk_gt_i32 s12, 0xbf
	s_waitcnt vmcnt(23)
	v_lshlrev_b32_e32 v68, 16, v42
	s_waitcnt vmcnt(22)
	v_lshlrev_b32_e32 v66, 16, v44
	s_waitcnt vmcnt(21)
	v_lshlrev_b32_e32 v62, 16, v46
	s_waitcnt vmcnt(20)
	v_lshlrev_b32_e32 v60, 16, v48
	v_and_b32_e32 v61, 0xffff0000, v48
	v_and_b32_e32 v63, 0xffff0000, v46
	v_lshlrev_b32_e32 v58, 16, v49
	v_and_b32_e32 v59, 0xffff0000, v49
	v_lshlrev_b32_e32 v48, 16, v47
	v_and_b32_e32 v49, 0xffff0000, v47
	v_mov_b32_e32 v46, v62
	v_mov_b32_e32 v47, v60
	v_mov_b32_e32 v64, v63
	v_mov_b32_e32 v65, v61
	v_pk_add_f32 v[46:47], v[46:47], v[64:65]
	v_mov_b32_e32 v64, v48
	v_mov_b32_e32 v65, v58
	v_pk_add_f32 v[46:47], v[46:47], v[64:65]
	v_mov_b32_e32 v64, v49
	v_mov_b32_e32 v65, v59
	v_and_b32_e32 v67, 0xffff0000, v44
	v_and_b32_e32 v69, 0xffff0000, v42
	v_pk_add_f32 v[46:47], v[46:47], v[64:65]
	v_lshlrev_b32_e32 v64, 16, v45
	v_and_b32_e32 v65, 0xffff0000, v45
	v_lshlrev_b32_e32 v44, 16, v43
	v_and_b32_e32 v45, 0xffff0000, v43
	v_mov_b32_e32 v42, v68
	v_mov_b32_e32 v43, v66
	v_mov_b32_e32 v70, v69
	v_mov_b32_e32 v71, v67
	v_pk_add_f32 v[42:43], v[42:43], v[70:71]
	v_mov_b32_e32 v70, v44
	v_mov_b32_e32 v71, v64
	v_pk_add_f32 v[42:43], v[42:43], v[70:71]
	v_mov_b32_e32 v70, v45
	v_mov_b32_e32 v71, v65
	s_waitcnt vmcnt(16)
	v_lshlrev_b32_e32 v72, 16, v56
	v_and_b32_e32 v73, 0xffff0000, v56
	v_lshlrev_b32_e32 v74, 16, v54
	v_and_b32_e32 v75, 0xffff0000, v54
	v_pk_add_f32 v[42:43], v[42:43], v[70:71]
	v_lshlrev_b32_e32 v70, 16, v57
	v_and_b32_e32 v71, 0xffff0000, v57
	v_lshlrev_b32_e32 v56, 16, v55
	v_and_b32_e32 v57, 0xffff0000, v55
	v_mov_b32_e32 v54, v74
	v_mov_b32_e32 v55, v72
	v_mov_b32_e32 v76, v75
	v_mov_b32_e32 v77, v73
	v_pk_add_f32 v[54:55], v[54:55], v[76:77]
	v_mov_b32_e32 v76, v56
	v_mov_b32_e32 v77, v70
	v_pk_add_f32 v[54:55], v[54:55], v[76:77]
	v_mov_b32_e32 v76, v57
	v_mov_b32_e32 v77, v71
	v_lshlrev_b32_e32 v78, 16, v52
	v_and_b32_e32 v79, 0xffff0000, v52
	v_lshlrev_b32_e32 v80, 16, v50
	v_and_b32_e32 v81, 0xffff0000, v50
	v_pk_add_f32 v[54:55], v[54:55], v[76:77]
	v_lshlrev_b32_e32 v76, 16, v53
	v_and_b32_e32 v77, 0xffff0000, v53
	v_lshlrev_b32_e32 v52, 16, v51
	v_and_b32_e32 v53, 0xffff0000, v51
	v_mov_b32_e32 v50, v80
	v_mov_b32_e32 v51, v78
	v_mov_b32_e32 v82, v81
	v_mov_b32_e32 v83, v79
	v_pk_add_f32 v[50:51], v[50:51], v[82:83]
	v_mov_b32_e32 v82, v52
	v_mov_b32_e32 v83, v76
	v_pk_add_f32 v[50:51], v[50:51], v[82:83]
	v_mov_b32_e32 v82, v53
	v_mov_b32_e32 v83, v77
	v_pk_add_f32 v[50:51], v[50:51], v[82:83]
	v_add_f32_e32 v42, 0, v42
	v_add_f32_e32 v50, 0, v50
	v_add_f32_e32 v42, v42, v43
	v_add_f32_e32 v50, v50, v51
	v_add_f32_e32 v42, v42, v46
	v_add_f32_e32 v50, v50, v54
	v_add_f32_e32 v42, v42, v47
	v_add_f32_e32 v50, v50, v55
	ds_bpermute_b32 v43, v35, v42
	ds_bpermute_b32 v51, v35, v50
	s_waitcnt lgkmcnt(1)
	v_add_f32_e32 v42, v42, v43
	s_waitcnt lgkmcnt(0)
	v_add_f32_e32 v50, v50, v51
	ds_bpermute_b32 v43, v39, v42
	ds_bpermute_b32 v51, v39, v50
	s_waitcnt lgkmcnt(1)
	v_add_f32_e32 v42, v42, v43
	s_waitcnt lgkmcnt(0)
	v_add_f32_e32 v50, v50, v51
	ds_bpermute_b32 v43, v86, v42
	ds_bpermute_b32 v51, v86, v50
	s_waitcnt lgkmcnt(1)
	v_add_f32_e32 v42, v42, v43
	s_waitcnt lgkmcnt(0)
	v_add_f32_e32 v50, v50, v51
	ds_bpermute_b32 v43, v87, v42
	ds_bpermute_b32 v51, v87, v50
	s_waitcnt lgkmcnt(1)
	v_add_f32_e32 v42, v42, v43
	s_waitcnt lgkmcnt(0)
	v_add_f32_e32 v50, v50, v51
	ds_bpermute_b32 v43, v88, v42
	ds_bpermute_b32 v51, v88, v50
	s_waitcnt lgkmcnt(1)
	v_add_f32_e32 v42, v42, v43
	s_waitcnt lgkmcnt(0)
	v_add_f32_e32 v50, v50, v51
	ds_bpermute_b32 v43, v89, v42
	ds_bpermute_b32 v51, v89, v50
	s_waitcnt lgkmcnt(1)
	v_add_f32_e32 v42, v42, v43
	s_waitcnt lgkmcnt(0)
	v_add_f32_e32 v50, v50, v51
	v_mul_f32_e32 v42, 0x3a800000, v42
	v_mul_f32_e32 v50, 0x3a800000, v50
	v_pk_add_f32 v[46:47], v[68:69], v[42:43] op_sel_hi:[1,0] neg_lo:[0,1] neg_hi:[0,1]
	v_pk_add_f32 v[80:81], v[80:81], v[50:51] op_sel_hi:[1,0] neg_lo:[0,1] neg_hi:[0,1]
	v_mov_b32_e32 v83, v47
	v_mov_b32_e32 v82, v81
	v_mov_b32_e32 v54, v80
	v_mov_b32_e32 v55, v46
	v_pk_mul_f32 v[82:83], v[82:83], v[82:83]
	v_pk_add_f32 v[44:45], v[44:45], v[42:43] op_sel_hi:[1,0] neg_lo:[0,1] neg_hi:[0,1]
	v_pk_fma_f32 v[54:55], v[54:55], v[54:55], v[82:83]
	v_pk_add_f32 v[82:83], v[52:53], v[50:51] op_sel_hi:[1,0] neg_lo:[0,1] neg_hi:[0,1]
	v_mov_b32_e32 v53, v44
	v_mov_b32_e32 v52, v82
	v_pk_add_f32 v[66:67], v[66:67], v[42:43] op_sel_hi:[1,0] neg_lo:[0,1] neg_hi:[0,1]
	v_pk_add_f32 v[78:79], v[78:79], v[50:51] op_sel_hi:[1,0] neg_lo:[0,1] neg_hi:[0,1]
	v_pk_fma_f32 v[52:53], v[52:53], v[52:53], v[54:55]
	v_mov_b32_e32 v54, v83
	v_mov_b32_e32 v55, v45
	v_pk_fma_f32 v[52:53], v[54:55], v[54:55], v[52:53]
	v_mov_b32_e32 v54, v78
	v_mov_b32_e32 v55, v66
	v_pk_add_f32 v[64:65], v[64:65], v[42:43] op_sel_hi:[1,0] neg_lo:[0,1] neg_hi:[0,1]
	v_pk_add_f32 v[76:77], v[76:77], v[50:51] op_sel_hi:[1,0] neg_lo:[0,1] neg_hi:[0,1]
	v_pk_fma_f32 v[52:53], v[54:55], v[54:55], v[52:53]
	v_mov_b32_e32 v54, v79
	v_mov_b32_e32 v55, v67
	v_pk_fma_f32 v[52:53], v[54:55], v[54:55], v[52:53]
	v_mov_b32_e32 v54, v76
	v_mov_b32_e32 v55, v64
	v_pk_add_f32 v[62:63], v[62:63], v[42:43] op_sel_hi:[1,0] neg_lo:[0,1] neg_hi:[0,1]
	v_pk_add_f32 v[74:75], v[74:75], v[50:51] op_sel_hi:[1,0] neg_lo:[0,1] neg_hi:[0,1]
	v_pk_fma_f32 v[52:53], v[54:55], v[54:55], v[52:53]
	v_mov_b32_e32 v54, v77
	v_mov_b32_e32 v55, v65
	v_pk_fma_f32 v[52:53], v[54:55], v[54:55], v[52:53]
	v_mov_b32_e32 v54, v74
	v_mov_b32_e32 v55, v62
	v_pk_add_f32 v[68:69], v[48:49], v[42:43] op_sel_hi:[1,0] neg_lo:[0,1] neg_hi:[0,1]
	v_pk_add_f32 v[84:85], v[56:57], v[50:51] op_sel_hi:[1,0] neg_lo:[0,1] neg_hi:[0,1]
	v_pk_fma_f32 v[52:53], v[54:55], v[54:55], v[52:53]
	v_mov_b32_e32 v54, v75
	v_mov_b32_e32 v55, v63
	v_pk_add_f32 v[60:61], v[60:61], v[42:43] op_sel_hi:[1,0] neg_lo:[0,1] neg_hi:[0,1]
	v_pk_add_f32 v[72:73], v[72:73], v[50:51] op_sel_hi:[1,0] neg_lo:[0,1] neg_hi:[0,1]
	v_pk_fma_f32 v[52:53], v[54:55], v[54:55], v[52:53]
	v_mov_b32_e32 v54, v84
	v_mov_b32_e32 v55, v68
	v_pk_mul_f32 v[48:49], v[60:61], v[60:61]
	v_pk_mul_f32 v[56:57], v[72:73], v[72:73]
	v_pk_fma_f32 v[52:53], v[54:55], v[54:55], v[52:53]
	v_mov_b32_e32 v54, v85
	v_mov_b32_e32 v55, v69
	v_pk_add_f32 v[42:43], v[58:59], v[42:43] op_sel_hi:[1,0] neg_lo:[0,1] neg_hi:[0,1]
	v_pk_fma_f32 v[52:53], v[54:55], v[54:55], v[52:53]
	v_mov_b32_e32 v54, v56
	v_mov_b32_e32 v55, v48
	v_pk_add_f32 v[70:71], v[70:71], v[50:51] op_sel_hi:[1,0] neg_lo:[0,1] neg_hi:[0,1]
	v_pk_mul_f32 v[58:59], v[42:43], v[42:43]
	v_pk_add_f32 v[52:53], v[54:55], v[52:53]
	v_pk_mul_f32 v[50:51], v[70:71], v[70:71]
	v_mov_b32_e32 v48, v57
	v_pk_add_f32 v[48:49], v[48:49], v[52:53]
	v_mov_b32_e32 v52, v50
	v_mov_b32_e32 v53, v58
	v_pk_add_f32 v[48:49], v[52:53], v[48:49]
	v_mov_b32_e32 v58, v51
	v_pk_add_f32 v[48:49], v[58:59], v[48:49]
	v_mov_b32_e32 v50, v48
	v_mov_b32_e32 v51, v49
	s_nop 1
	v_permlane32_swap_b32_e32 v50, v48
	v_permlane32_swap_b32_e32 v51, v49
	v_pk_add_f32 v[48:49], v[48:49], v[50:51]
	v_mov_b32_e32 v50, v48
	v_mov_b32_e32 v51, v49
	s_nop 1
	v_permlane16_swap_b32_e32 v50, v48
	v_permlane16_swap_b32_e32 v51, v49
	v_pk_add_f32 v[48:49], v[48:49], v[50:51]
	s_nop 1
	v_add_f32_dpp v48, v48, v48 row_ror:8 row_mask:0xf bank_mask:0xf
	v_add_f32_dpp v49, v49, v49 row_ror:8 row_mask:0xf bank_mask:0xf
	s_nop 0
	v_add_f32_dpp v48, v48, v48 row_ror:4 row_mask:0xf bank_mask:0xf
	v_add_f32_dpp v49, v49, v49 row_ror:4 row_mask:0xf bank_mask:0xf
	s_nop 0
	v_add_f32_dpp v48, v48, v48 row_ror:2 row_mask:0xf bank_mask:0xf
	v_add_f32_dpp v49, v49, v49 row_ror:2 row_mask:0xf bank_mask:0xf
	s_nop 0
	v_add_f32_dpp v48, v48, v48 row_ror:1 row_mask:0xf bank_mask:0xf
	v_add_f32_dpp v49, v49, v49 row_ror:1 row_mask:0xf bank_mask:0xf
	s_nop 0
	v_pk_fma_f32 v[58:59], v[48:49], s[24:25], v[138:139] op_sel_hi:[1,0,0]
	s_nop 0
	v_mul_f32_e32 v35, 0x4b800000, v59
	v_cmp_gt_f32_e64 s[0:1], s33, v59
	v_cmp_gt_f32_e32 vcc, s33, v58
	s_nop 0
	v_cndmask_b32_e64 v35, v59, v35, s[0:1]
	v_rsq_f32_e32 v35, v35
	s_nop 0
	v_mul_f32_e32 v39, 0x45800000, v35
	v_cndmask_b32_e64 v86, v35, v39, s[0:1]
	v_mul_f32_e32 v35, 0x4b800000, v58
	v_cndmask_b32_e32 v35, v58, v35, vcc
	v_rsq_f32_e32 v35, v35
	v_pk_mul_f32 v[44:45], v[44:45], v[86:87] op_sel_hi:[1,0]
	v_pk_mul_f32 v[46:47], v[46:47], v[86:87] op_sel_hi:[1,0]
	s_waitcnt vmcnt(14)
	v_pk_fma_f32 v[54:55], v[26:27], v[44:45], v[30:31]
	v_pk_mul_f32 v[44:45], v[66:67], v[86:87] op_sel_hi:[1,0]
	v_mul_f32_e32 v39, 0x45800000, v35
	s_waitcnt vmcnt(12)
	v_pk_fma_f32 v[52:53], v[16:17], v[44:45], v[20:21]
	v_pk_mul_f32 v[44:45], v[64:65], v[86:87] op_sel_hi:[1,0]
	v_cndmask_b32_e32 v58, v35, v39, vcc
	v_pk_fma_f32 v[50:51], v[18:19], v[44:45], v[22:23]
	v_pk_mul_f32 v[44:45], v[62:63], v[86:87] op_sel_hi:[1,0]
	v_pk_fma_f32 v[56:57], v[24:25], v[46:47], v[28:29]
	s_waitcnt vmcnt(10)
	v_pk_fma_f32 v[48:49], v[8:9], v[44:45], v[12:13]
	v_pk_mul_f32 v[44:45], v[68:69], v[86:87] op_sel_hi:[1,0]
	v_pk_mul_f32 v[42:43], v[42:43], v[86:87] op_sel_hi:[1,0]
	v_pk_fma_f32 v[46:47], v[10:11], v[44:45], v[14:15]
	v_pk_mul_f32 v[44:45], v[60:61], v[86:87] op_sel_hi:[1,0]
	v_pk_mul_f32 v[60:61], v[80:81], v[58:59] op_sel_hi:[1,0]
	s_waitcnt vmcnt(8)
	v_pk_fma_f32 v[44:45], v[0:1], v[44:45], v[4:5]
	v_pk_fma_f32 v[24:25], v[24:25], v[60:61], v[28:29]
	v_pk_mul_f32 v[28:29], v[82:83], v[58:59] op_sel_hi:[1,0]
	v_pk_fma_f32 v[42:43], v[2:3], v[42:43], v[6:7]
	v_pk_fma_f32 v[26:27], v[26:27], v[28:29], v[30:31]
	v_pk_mul_f32 v[28:29], v[78:79], v[58:59] op_sel_hi:[1,0]
	v_cmp_lt_i32_e32 vcc, s17, v38
	v_pk_fma_f32 v[16:17], v[16:17], v[28:29], v[20:21]
	v_pk_mul_f32 v[20:21], v[76:77], v[58:59] op_sel_hi:[1,0]
	s_nop 0
	v_pk_fma_f32 v[18:19], v[18:19], v[20:21], v[22:23]
	v_pk_mul_f32 v[20:21], v[74:75], v[58:59] op_sel_hi:[1,0]
	s_nop 0
	v_pk_fma_f32 v[8:9], v[8:9], v[20:21], v[12:13]
	v_pk_mul_f32 v[12:13], v[84:85], v[58:59] op_sel_hi:[1,0]
	s_nop 0
	v_pk_fma_f32 v[10:11], v[10:11], v[12:13], v[14:15]
	v_pk_mul_f32 v[12:13], v[72:73], v[58:59] op_sel_hi:[1,0]
	s_nop 0
	v_pk_fma_f32 v[0:1], v[0:1], v[12:13], v[4:5]
	v_pk_mul_f32 v[4:5], v[70:71], v[58:59] op_sel_hi:[1,0]
	s_nop 0
	v_pk_fma_f32 v[2:3], v[2:3], v[4:5], v[6:7]
	s_waitcnt vmcnt(0)
	v_mov_b64_e32 v[4:5], v[206:207]
	v_mov_b64_e32 v[6:7], v[208:209]
	v_mov_b64_e32 v[12:13], v[214:215]
	v_mov_b64_e32 v[14:15], v[216:217]
	v_mov_b64_e32 v[20:21], v[218:219]
	v_mov_b64_e32 v[22:23], v[220:221]
	v_mov_b64_e32 v[28:29], v[222:223]
	v_mov_b64_e32 v[30:31], v[224:225]
	v_mov_b64_e32 v[58:59], v[226:227]
	v_mov_b64_e32 v[60:61], v[228:229]
	v_mov_b64_e32 v[62:63], v[230:231]
	v_mov_b64_e32 v[64:65], v[232:233]
	v_mov_b64_e32 v[66:67], v[234:235]
	v_mov_b64_e32 v[68:69], v[236:237]
	v_mov_b64_e32 v[70:71], v[238:239]
	v_mov_b64_e32 v[72:73], v[240:241]
	v_cvt_pk_bf16_f32 v40, v56, v57
	v_cvt_pk_bf16_f32 v41, v54, v55
	global_store_dwordx2 v[36:37], v[40:41], off

	v_pk_add_f32 v[12:13], v[12:13], 1.0 op_sel_hi:[1,0]
	v_pk_add_f32 v[14:15], v[14:15], 1.0 op_sel_hi:[1,0]
	v_pk_fma_f32 v[40:41], v[12:13], v[56:57], v[4:5]
	v_pk_fma_f32 v[54:55], v[14:15], v[54:55], v[6:7]
	v_cvt_pk_bf16_f32 v40, v40, v41
	v_cvt_pk_bf16_f32 v41, v54, v55
	v_mov_b64_e32 v[54:55], s[62:63]
	v_mad_i64_i32 v[38:39], s[0:1], v38, s36, v[54:55]
	v_lshl_add_u64 v[38:39], v[38:39], 0, v[136:137]
	global_store_dwordx2 v[38:39], v[40:41], off
	v_cvt_pk_bf16_f32 v40, v52, v53
	v_cvt_pk_bf16_f32 v41, v50, v51

	v_pk_add_f32 v[28:29], v[28:29], 1.0 op_sel_hi:[1,0]
	v_pk_add_f32 v[30:31], v[30:31], 1.0 op_sel_hi:[1,0]
	global_store_dwordx2 v[36:37], v[40:41], off offset:512
	v_pk_fma_f32 v[40:41], v[28:29], v[52:53], v[20:21]
	v_pk_fma_f32 v[50:51], v[30:31], v[50:51], v[22:23]
	v_cvt_pk_bf16_f32 v40, v40, v41
	v_cvt_pk_bf16_f32 v41, v50, v51
	global_store_dwordx2 v[38:39], v[40:41], off offset:512
	v_cvt_pk_bf16_f32 v40, v48, v49
	v_cvt_pk_bf16_f32 v41, v46, v47
	global_store_dwordx2 v[36:37], v[40:41], off offset:1024

	v_pk_add_f32 v[40:41], v[62:63], 1.0 op_sel_hi:[1,0]
	v_pk_add_f32 v[50:51], v[64:65], 1.0 op_sel_hi:[1,0]
	v_pk_fma_f32 v[48:49], v[40:41], v[48:49], v[58:59]
	v_pk_fma_f32 v[46:47], v[50:51], v[46:47], v[60:61]
	v_cvt_pk_bf16_f32 v48, v48, v49
	v_cvt_pk_bf16_f32 v49, v46, v47
	v_cvt_pk_bf16_f32 v46, v44, v45
	v_cvt_pk_bf16_f32 v47, v42, v43
	global_store_dwordx2 v[38:39], v[48:49], off offset:1024
	global_store_dwordx2 v[36:37], v[46:47], off offset:1536

	v_pk_add_f32 v[36:37], v[70:71], 1.0 op_sel_hi:[1,0]
	v_pk_add_f32 v[46:47], v[72:73], 1.0 op_sel_hi:[1,0]
	v_pk_fma_f32 v[44:45], v[36:37], v[44:45], v[66:67]
	v_pk_fma_f32 v[42:43], v[46:47], v[42:43], v[68:69]
	v_pk_fma_f32 v[4:5], v[12:13], v[24:25], v[4:5]
	v_pk_fma_f32 v[6:7], v[14:15], v[26:27], v[6:7]
	v_cvt_pk_bf16_f32 v44, v44, v45
	v_cvt_pk_bf16_f32 v45, v42, v43
	v_cvt_pk_bf16_f32 v4, v4, v5
	v_cvt_pk_bf16_f32 v5, v6, v7
	v_mad_i64_i32 v[6:7], s[0:1], v34, s36, v[54:55]
	global_store_dwordx2 v[38:39], v[44:45], off offset:1536
	v_cvt_pk_bf16_f32 v38, v24, v25
	v_cvt_pk_bf16_f32 v39, v26, v27
	v_lshl_add_u64 v[6:7], v[6:7], 0, v[136:137]
	global_store_dwordx2 v[32:33], v[38:39], off
	global_store_dwordx2 v[6:7], v[4:5], off
	v_cvt_pk_bf16_f32 v4, v16, v17
	v_cvt_pk_bf16_f32 v5, v18, v19
	global_store_dwordx2 v[32:33], v[4:5], off offset:512
	v_pk_fma_f32 v[4:5], v[28:29], v[16:17], v[20:21]
	v_pk_fma_f32 v[12:13], v[30:31], v[18:19], v[22:23]
	v_cvt_pk_bf16_f32 v4, v4, v5
	v_cvt_pk_bf16_f32 v5, v12, v13
	global_store_dwordx2 v[6:7], v[4:5], off offset:512
	v_cvt_pk_bf16_f32 v4, v8, v9
	v_cvt_pk_bf16_f32 v5, v10, v11
	global_store_dwordx2 v[32:33], v[4:5], off offset:1024
	v_pk_fma_f32 v[4:5], v[40:41], v[8:9], v[58:59]
	v_pk_fma_f32 v[8:9], v[50:51], v[10:11], v[60:61]
	v_cvt_pk_bf16_f32 v4, v4, v5
	v_cvt_pk_bf16_f32 v5, v8, v9
	global_store_dwordx2 v[6:7], v[4:5], off offset:1024
	v_cvt_pk_bf16_f32 v4, v0, v1
	v_cvt_pk_bf16_f32 v5, v2, v3
	v_pk_fma_f32 v[0:1], v[36:37], v[0:1], v[66:67]
	v_pk_fma_f32 v[2:3], v[46:47], v[2:3], v[68:69]
	v_cvt_pk_bf16_f32 v0, v0, v1
	v_cvt_pk_bf16_f32 v1, v2, v3
	global_store_dwordx2 v[32:33], v[4:5], off offset:1536
	global_store_dwordx2 v[6:7], v[0:1], off offset:1536
	s_cbranch_scc0 .LBB0_1056
